# attention: third K tile and second V tile of the next unit prefetched too, merge buffers moved again (one barrier before the merge)
# baseline (speedup 1.0000x reference)
.LBB0_625:
	s_add_u32 s4, s0, s14
	s_addc_u32 s5, s1, s15
	global_load_dwordx4 v[4:7], v193, s[4:5] offset:48
	global_load_dwordx4 v[8:11], v193, s[4:5] offset:32
	global_load_dwordx4 v[12:15], v193, s[4:5] offset:16
	global_load_dwordx4 v[16:19], v193, s[4:5]
	global_load_dwordx4 v[20:23], v193, s[4:5] offset:304
	global_load_dwordx4 v[24:27], v193, s[4:5] offset:288
	global_load_dwordx4 v[28:31], v193, s[4:5] offset:272
	global_load_dwordx4 v[32:35], v193, s[4:5] offset:256
	global_load_dwordx4 v[36:39], v193, s[4:5] offset:560
	global_load_dwordx4 v[40:43], v193, s[4:5] offset:544
	global_load_dwordx4 v[44:47], v193, s[4:5] offset:528
	global_load_dwordx4 v[48:51], v193, s[4:5] offset:512
	global_load_dwordx4 v[52:55], v193, s[4:5] offset:816
	global_load_dwordx4 v[56:59], v193, s[4:5] offset:800
	global_load_dwordx4 v[60:63], v193, s[4:5] offset:784
	global_load_dwordx4 v[64:67], v193, s[4:5] offset:768
	s_add_u32 s14, s14, 64
	s_addc_u32 s15, s15, 0
	s_cmpk_eq_i32 s14, 0x100
	s_waitcnt vmcnt(12)
	v_mov_b32_e32 v68, v16
	v_mov_b32_e32 v16, v18
	s_waitcnt vmcnt(9)
	v_mov_b32_e32 v18, v28
	s_waitcnt vmcnt(8)
	v_mov_b32_e32 v70, v32
	v_mov_b32_e32 v32, v34
	s_waitcnt vmcnt(4)
	v_mov_b32_e32 v69, v48
	v_mov_b32_e32 v48, v17
	v_mov_b32_e32 v17, v50
	v_mov_b32_e32 v50, v19
	s_waitcnt vmcnt(0)
	v_mov_b32_e32 v71, v64
	v_pk_fma_f32 v[0:1], v[68:69], v[70:71], v[0:1]
	v_mov_b32_e32 v64, v33
	v_pk_fma_f32 v[0:1], v[48:49], v[64:65], v[0:1]
	v_mov_b32_e32 v33, v66
	v_pk_fma_f32 v[0:1], v[16:17], v[32:33], v[0:1]
	v_mov_b32_e32 v66, v35
	v_pk_fma_f32 v[0:1], v[50:51], v[66:67], v[0:1]
	v_mov_b32_e32 v16, v12
	v_mov_b32_e32 v17, v44
	v_mov_b32_e32 v19, v60
	v_pk_fma_f32 v[0:1], v[16:17], v[18:19], v[0:1]
	v_mov_b32_e32 v44, v13
	v_mov_b32_e32 v60, v29
	v_pk_fma_f32 v[0:1], v[44:45], v[60:61], v[0:1]
	v_mov_b32_e32 v12, v14
	v_mov_b32_e32 v13, v46
	v_mov_b32_e32 v16, v30
	v_mov_b32_e32 v17, v62
	v_pk_fma_f32 v[0:1], v[12:13], v[16:17], v[0:1]
	v_mov_b32_e32 v46, v15
	v_mov_b32_e32 v62, v31
	v_pk_fma_f32 v[0:1], v[46:47], v[62:63], v[0:1]
	v_mov_b32_e32 v12, v8
	v_mov_b32_e32 v13, v40
	v_mov_b32_e32 v14, v24
	v_mov_b32_e32 v15, v56
	v_pk_fma_f32 v[0:1], v[12:13], v[14:15], v[0:1]
	v_mov_b32_e32 v40, v9
	v_mov_b32_e32 v56, v25
	v_pk_fma_f32 v[0:1], v[40:41], v[56:57], v[0:1]
	v_mov_b32_e32 v8, v10
	v_mov_b32_e32 v9, v42
	v_mov_b32_e32 v12, v26
	v_mov_b32_e32 v13, v58
	v_pk_fma_f32 v[0:1], v[8:9], v[12:13], v[0:1]
	v_mov_b32_e32 v42, v11
	v_mov_b32_e32 v58, v27
	v_pk_fma_f32 v[0:1], v[42:43], v[58:59], v[0:1]
	v_mov_b32_e32 v8, v4
	v_mov_b32_e32 v9, v36
	v_mov_b32_e32 v10, v20
	v_mov_b32_e32 v11, v52
	v_pk_fma_f32 v[0:1], v[8:9], v[10:11], v[0:1]
	v_mov_b32_e32 v36, v5
	v_mov_b32_e32 v52, v21
	v_pk_fma_f32 v[0:1], v[36:37], v[52:53], v[0:1]
	v_mov_b32_e32 v4, v6
	v_mov_b32_e32 v5, v38
	v_mov_b32_e32 v8, v22
	v_mov_b32_e32 v9, v54
	v_pk_fma_f32 v[0:1], v[4:5], v[8:9], v[0:1]
	v_mov_b32_e32 v38, v7
	v_mov_b32_e32 v54, v23
	v_pk_fma_f32 v[0:1], v[38:39], v[54:55], v[0:1]
	s_cbranch_scc0 .LBB0_625
	v_readfirstlane_b32 s0, v3
	s_cmpk_gt_i32 s0, 0x3ff
	s_cbranch_scc1 .LBB0_654
	v_readlane_b32 s14, v252, 1
	s_mov_b32 s1, 0x3fb8aa3b
	s_mov_b32 s4, 0xc2ce8ed0
	v_cvt_f32_u32_e32 v3, s14
	s_mov_b32 s5, 0x42b17218
	s_add_u32 s6, s6, 0x5720000
	s_addc_u32 s7, s7, 0
	v_mul_f32_e32 v3, 0xbe99999a, v3
	v_mul_f32_e32 v4, 0x3fb8aa3b, v3
	v_fma_f32 v5, v3, s1, -v4
	v_rndne_f32_e32 v6, v4
	v_fmac_f32_e32 v5, 0x32a5705f, v3
	v_sub_f32_e32 v4, v4, v6
	v_add_f32_e32 v4, v4, v5
	v_cvt_i32_f32_e32 v6, v6
	v_exp_f32_e32 v4, v4
	v_cmp_ngt_f32_e32 vcc, s4, v3
	s_add_u32 s10, s10, 0x9b20000
	s_addc_u32 s11, s11, 0
	v_ldexp_f32 v4, v4, v6
	v_cndmask_b32_e32 v4, 0, v4, vcc
	v_cmp_nlt_f32_e32 vcc, s5, v3
	v_readlane_b32 s15, v252, 2
	s_add_u32 s12, s12, 0x3700000
	v_cndmask_b32_e32 v3, v241, v4, vcc
	v_mul_f32_e32 v4, 0x3fb8aa3b, v0
	v_rndne_f32_e32 v5, v4
	v_sub_f32_e32 v6, v4, v5
	v_fma_f32 v4, v0, s1, -v4
	v_fmac_f32_e32 v4, 0x32a5705f, v0
	v_add_f32_e32 v4, v6, v4
	v_exp_f32_e32 v4, v4
	v_cvt_i32_f32_e32 v5, v5
	v_cmp_ngt_f32_e32 vcc, s4, v0
	s_addc_u32 s13, s13, 0
	s_ashr_i32 s28, s2, 8
	v_ldexp_f32 v4, v4, v5
	v_mul_f32_e32 v5, 0x3fb8aa3b, v1
	v_rndne_f32_e32 v6, v5
	v_sub_f32_e32 v7, v5, v6
	v_fma_f32 v5, v1, s1, -v5
	v_fmac_f32_e32 v5, 0x32a5705f, v1
	v_add_f32_e32 v5, v7, v5
	v_exp_f32_e32 v5, v5
	v_cvt_i32_f32_e32 v6, v6
	v_cndmask_b32_e32 v4, 0, v4, vcc
	v_cmp_nlt_f32_e32 vcc, s5, v0
	s_ashr_i32 s16, s2, 6
	v_fmamk_f32 v3, v3, 0xbf19999a, v239
	v_cndmask_b32_e32 v0, v241, v4, vcc
	v_ldexp_f32 v4, v5, v6
	v_cmp_ngt_f32_e32 vcc, s4, v1
	v_sub_f32_e32 v176, 1.0, v3
	v_and_b32_e32 v7, 63, v2
	v_cndmask_b32_e32 v4, 0, v4, vcc
	v_cmp_nlt_f32_e32 vcc, s5, v1
	s_lshl_b64 s[4:5], s[14:15], 9
	s_add_u32 s26, s42, s4
	s_addc_u32 s27, s43, s5
	s_lshl_b32 s1, s0, 1
	s_and_b32 s1, s1, 14
	s_ashr_i32 s4, s0, 7
	s_lshl_b32 s14, s28, 6
	s_lshl_b32 s5, s16, 10
	v_cndmask_b32_e32 v1, v241, v4, vcc
	s_and_b32 s30, s16, 3
	s_add_i32 s1, s1, s4
	s_lshr_b32 s4, s0, 3
	s_ashr_i32 s15, s14, 31
	s_add_i32 s5, s5, 0
	v_sub_f32_e32 v0, v0, v1
	s_cmpk_lt_u32 s2, 0x100
	v_add_f32_e32 v177, v3, v0
	v_lshrrev_b32_e32 v3, 1, v2
	v_lshlrev_b32_e32 v0, 1, v2
	s_cselect_b64 s[16:17], -1, 0
	s_lshl_b32 s2, s28, 13
	v_and_b32_e32 v0, 8, v0
	v_and_b32_e32 v4, 19, v2
	v_and_b32_e32 v6, 4, v3
	s_add_i32 s2, s2, 0
	v_and_b32_e32 v1, 31, v2
	v_or3_b32 v4, v0, v4, v6
	s_cmp_eq_u32 s28, 1
	v_lshl_or_b32 v178, s30, 5, v1
	v_lshl_add_u32 v179, v4, 7, s2
	s_cselect_b64 s[28:29], -1, 0
	v_lshlrev_b32_e32 v1, 7, v1
	s_add_i32 s2, 0, 0x1c000
	v_add_u32_e32 v180, s2, v1
	s_mov_b32 s2, 0xc000
	s_cmp_eq_u32 s30, 1
	s_cselect_b32 s2, 0x18000, s2
	s_cmp_eq_u32 s30, 2
	s_cselect_b32 s2, 0x1c000, s2
	s_cmp_eq_u32 s30, 3
	s_cselect_b32 s2, 0x20010, s2
	v_lshrrev_b32_e32 v6, 1, v4
	v_bfe_u32 v8, v2, 5, 1
	s_add_i32 s2, s2, 0
	v_lshl_add_u32 v181, v7, 2, s2
	v_bitop3_b32 v7, v6, v8, 7 bitop3:0x6c
	v_lshlrev_b32_e32 v182, 4, v7
	v_or_b32_e32 v7, 2, v8
	v_bitop3_b32 v7, v6, v7, 7 bitop3:0x6c
	v_lshlrev_b32_e32 v183, 4, v7
	v_or_b32_e32 v7, 4, v8
	v_lshrrev_b32_e32 v9, 4, v2
	v_bitop3_b32 v7, v6, v7, 7 bitop3:0x6c
	v_ashrrev_i32_e32 v160, 3, v2
	v_bfe_u32 v5, v2, 1, 3
	v_xor_b32_e32 v2, v9, v2
	v_lshlrev_b32_e32 v184, 4, v7
	v_or_b32_e32 v7, 6, v8
	v_bitop3_b32 v3, v8, v3, 7 bitop3:0x78
	v_lshlrev_b32_e32 v2, 3, v2
	v_bitop3_b32 v6, v6, v7, 7 bitop3:0x6c
	v_lshlrev_b32_e32 v187, 4, v3
	v_bitop3_b32 v3, v8, v5, 2 bitop3:0x36
	v_lshlrev_b32_e32 v0, 3, v8
	v_and_b32_e32 v2, 56, v2
	v_lshlrev_b32_e32 v4, 2, v8
	v_lshlrev_b32_e32 v192, 4, v8
	v_lshlrev_b32_e32 v185, 4, v6
	v_bitop3_b32 v6, v8, v5, 4 bitop3:0x36
	v_lshlrev_b32_e32 v188, 4, v3
	v_bitop3_b32 v3, v8, v5, 6 bitop3:0x36
	v_ashrrev_i32_e32 v161, 31, v160
	v_lshl_add_u64 v[162:163], s[26:27], 0, v[192:193]
	s_add_i32 s26, s5, 0x10000
	s_add_i32 s27, s5, 0x12000
	s_add_i32 s34, s5, 0x14000
	s_add_i32 s35, s5, 0x16000
	s_add_i32 s36, s5, 0x18000
	s_add_i32 s37, s5, 0x1a000
	s_add_i32 s44, s5, 0x1c000
	s_add_i32 s45, s5, 0x1e000
	v_lshlrev_b32_e32 v186, 4, v6
	v_lshlrev_b32_e32 v189, 4, v3
	v_add_u32_e32 v190, 0, v1
	s_mov_b32 s46, 0
	v_lshlrev_b32_e32 v192, 1, v0
	v_lshlrev_b32_e32 v164, 1, v2
	v_lshlrev_b32_e32 v166, 1, v4
	v_add_u32_e32 v182, v179, v182
	v_add_u32_e32 v183, v179, v183
	v_add_u32_e32 v184, v179, v184
	v_add_u32_e32 v185, v179, v185
	v_add_u32_e32 v187, v190, v187
	v_add_u32_e32 v188, v190, v188
	v_add_u32_e32 v186, v190, v186
	v_add_u32_e32 v189, v190, v189
	v_add_u32_e32 v187, 0x10000, v187
	v_add_u32_e32 v188, 0x10000, v188
	v_add_u32_e32 v186, 0x10000, v186
	v_add_u32_e32 v189, 0x10000, v189
	s_add_u32 s26, s6, 0x800
	s_addc_u32 s27, s7, 0
	s_mov_b32 s35, 0
	s_mov_b32 s2, s0
	s_branch .LBB0_629

.Lattn_skipq:
	v_lshl_add_u64 v[2:3], s[42:43], 0, v[160:161]
	v_mov_b32_e32 v169, s43
	v_mad_u64_u32 v[0:1], s[42:43], v2, s47, v[0:1]
	v_mad_i32_i24 v1, v3, s47, v1
	v_lshl_add_u64 v[0:1], v[0:1], 0, s[30:31]
	v_mov_b32_e32 v165, v193
	v_lshl_add_u64 v[170:171], v[0:1], 0, v[164:165]
	v_add_u32_e32 v2, s2, v160
	v_mov_b64_e32 v[0:1], s[10:11]
	v_mad_i64_i32 v[0:1], s[42:43], v2, s73, v[0:1]
	s_lshl_b64 s[40:41], s[40:41], 12
	v_lshl_add_u64 v[0:1], v[0:1], 0, s[40:41]
	s_mul_i32 s2, s38, 0x88000
	v_lshl_add_u64 v[172:173], v[0:1], 0, v[164:165]
	s_lshl_b32 s31, s38, 1
	s_not_b64 s[38:39], s[16:17]
	v_and_b32_e32 v34, 64, v240
	v_xor_b32_e32 v33, 32, v240
	v_add_u32_e32 v34, 64, v34
	v_cmp_lt_i32_e32 vcc, v33, v34
	s_nop 1
	v_cndmask_b32_e32 v33, v240, v33, vcc
	v_lshlrev_b32_e32 v165, 2, v33
	s_mov_b32 s42, s31
	v_subrev_u32_e32 v170, s6, v170
	v_subrev_u32_e32 v172, s10, v172
	s_cmp_lg_u32 s35, 0
	s_cbranch_scc0 .Lattn_pro_np
	s_add_i32 s2, s42, 3
	s_and_b32 s2, s2, 31
	s_mul_i32 s2, s2, 0x44000
	s_add_i32 m0, s5, 49152
	s_add_u32 s40, s26, s2
	s_addc_u32 s41, s27, 0
	global_load_lds_dwordx4 v170, s[40:41]
	s_add_i32 m0, s5, 57344
	s_add_u32 s40, s40, 0x80
	s_addc_u32 s41, s41, 0
	global_load_lds_dwordx4 v170, s[40:41]
	v_mov_b32_e32 v128, v144
	v_mov_b32_e32 v129, v145
	v_mov_b32_e32 v130, v146
	v_mov_b32_e32 v131, v147
	v_mov_b32_e32 v132, v148
	v_mov_b32_e32 v133, v149
	v_mov_b32_e32 v134, v150
	v_mov_b32_e32 v135, v151
	v_mov_b32_e32 v0, 0
	v_mov_b32_e32 v1, 0
	v_mov_b32_e32 v2, 0
	v_mov_b32_e32 v3, 0
	v_mov_b32_e32 v4, 0
	v_mov_b32_e32 v5, 0
	v_mov_b32_e32 v6, 0
	v_mov_b32_e32 v7, 0
	v_mov_b32_e32 v8, 0
	v_mov_b32_e32 v9, 0
	v_mov_b32_e32 v10, 0
	v_mov_b32_e32 v11, 0
	v_mov_b32_e32 v12, 0
	v_mov_b32_e32 v13, 0
	v_mov_b32_e32 v14, 0
	v_mov_b32_e32 v15, 0
	v_mov_b32_e32 v16, 0
	v_mov_b32_e32 v17, 0
	v_mov_b32_e32 v18, 0
	v_mov_b32_e32 v19, 0
	v_mov_b32_e32 v20, 0
	v_mov_b32_e32 v21, 0
	v_mov_b32_e32 v22, 0
	v_mov_b32_e32 v23, 0
	v_mov_b32_e32 v24, 0
	v_mov_b32_e32 v25, 0
	v_mov_b32_e32 v26, 0
	v_mov_b32_e32 v27, 0
	v_mov_b32_e32 v28, 0
	v_mov_b32_e32 v29, 0
	v_mov_b32_e32 v30, 0
	v_mov_b32_e32 v31, 0
	v_mov_b32_e32 v32, 0
	v_mov_b32_e32 v33, 0
	v_mov_b32_e32 v34, 0
	v_mov_b32_e32 v35, 0
	v_mov_b32_e32 v36, 0
	v_mov_b32_e32 v37, 0
	v_mov_b32_e32 v38, 0
	v_mov_b32_e32 v39, 0
	v_mov_b32_e32 v40, 0
	v_mov_b32_e32 v41, 0
	v_mov_b32_e32 v42, 0
	v_mov_b32_e32 v43, 0
	v_mov_b32_e32 v44, 0
	v_mov_b32_e32 v45, 0
	v_mov_b32_e32 v46, 0
	v_mov_b32_e32 v47, 0
	v_mov_b32_e32 v48, 0
	v_mov_b32_e32 v49, 0
	v_mov_b32_e32 v50, 0
	v_mov_b32_e32 v51, 0
	v_mov_b32_e32 v52, 0
	v_mov_b32_e32 v53, 0
	v_mov_b32_e32 v54, 0
	v_mov_b32_e32 v55, 0
	v_mov_b32_e32 v56, 0
	v_mov_b32_e32 v57, 0
	v_mov_b32_e32 v58, 0
	v_mov_b32_e32 v59, 0
	v_mov_b32_e32 v60, 0
	v_mov_b32_e32 v61, 0
	v_mov_b32_e32 v62, 0
	v_mov_b32_e32 v63, 0
	v_mov_b32_e32 v167, 0
	v_mov_b32_e32 v175, 0
	v_mov_b32_e32 v174, 1.0
	s_waitcnt vmcnt(2)
	s_branch .Lattn_pro_join

.Lattn_pfvt_f:
	v_add_f32_e32 v190, v190, v234
	v_add_f32_e32 v191, v191, v235
	v_cvt_pk_bf16_f32 v144, v171, v173
	s_cmp_lg_u32 s35, 0
	s_cbranch_scc0 .Lattn_pfkc_f
	s_add_i32 s2, s31, 2
	s_and_b32 s2, s2, 31
	s_mul_i32 s2, s2, 0x44000
	s_add_i32 m0, s5, 32768
	s_add_u32 s40, s26, s2
	s_addc_u32 s41, s27, 0
	s_add_u32 s40, s40, 0x1100000
	s_addc_u32 s41, s41, 0
	global_load_lds_dwordx4 v170, s[40:41]
	s_add_i32 m0, s5, 40960
	s_add_u32 s40, s40, 0x80
	s_addc_u32 s41, s41, 0
	global_load_lds_dwordx4 v170, s[40:41]
.Lattn_pfkc_f:
	v_cvt_pk_bf16_f32 v145, v179, v180
	v_cvt_pk_bf16_f32 v146, v232, v233
	v_cvt_pk_bf16_f32 v147, v234, v235
	v_exp_f32_e32 v171, v72
	v_exp_f32_e32 v173, v73
	v_exp_f32_e32 v179, v74
	v_exp_f32_e32 v180, v75
	v_exp_f32_e32 v232, v76
	v_exp_f32_e32 v233, v77
	v_exp_f32_e32 v234, v78
	v_exp_f32_e32 v235, v79
	v_add_f32_e32 v190, v190, v171
	v_add_f32_e32 v191, v191, v173
	v_add_f32_e32 v190, v190, v179
	v_add_f32_e32 v191, v191, v180
	v_add_f32_e32 v190, v190, v232
	v_add_f32_e32 v191, v191, v233
	v_add_f32_e32 v190, v190, v234
	v_add_f32_e32 v191, v191, v235
	v_cvt_pk_bf16_f32 v148, v171, v173
	v_cvt_pk_bf16_f32 v149, v179, v180
	v_cvt_pk_bf16_f32 v150, v232, v233
	v_cvt_pk_bf16_f32 v151, v234, v235
	v_exp_f32_e32 v171, v80
	v_exp_f32_e32 v173, v81
	v_exp_f32_e32 v179, v82
	v_exp_f32_e32 v180, v83
	v_exp_f32_e32 v232, v84
	v_exp_f32_e32 v233, v85
	v_exp_f32_e32 v234, v86
	v_exp_f32_e32 v235, v87
	v_add_f32_e32 v190, v190, v171
	v_add_f32_e32 v191, v191, v173
	v_add_f32_e32 v190, v190, v179
	v_add_f32_e32 v191, v191, v180
	v_add_f32_e32 v190, v190, v232
	v_add_f32_e32 v191, v191, v233
	v_add_f32_e32 v190, v190, v234
	v_add_f32_e32 v191, v191, v235
	v_cvt_pk_bf16_f32 v152, v171, v173
	v_cvt_pk_bf16_f32 v153, v179, v180
	v_cvt_pk_bf16_f32 v154, v232, v233
	v_cvt_pk_bf16_f32 v155, v234, v235
	v_exp_f32_e32 v171, v88
	v_exp_f32_e32 v173, v89
	v_exp_f32_e32 v179, v90
	v_exp_f32_e32 v180, v91
	v_exp_f32_e32 v232, v92
	v_exp_f32_e32 v233, v93
	v_exp_f32_e32 v234, v94
	v_exp_f32_e32 v235, v95
	v_add_f32_e32 v190, v190, v171
	v_add_f32_e32 v191, v191, v173
	v_add_f32_e32 v190, v190, v179
	v_add_f32_e32 v191, v191, v180
	v_add_f32_e32 v190, v190, v232
	v_add_f32_e32 v191, v191, v233
	v_add_f32_e32 v190, v190, v234
	v_add_f32_e32 v191, v191, v235
	v_add_f32_e32 v190, v190, v191
	v_cmp_ngt_f32_e32 vcc, 0x71800000, v190
	v_cvt_pk_bf16_f32 v156, v171, v173
	v_cvt_pk_bf16_f32 v157, v179, v180
	v_cvt_pk_bf16_f32 v158, v232, v233
	v_cvt_pk_bf16_f32 v159, v234, v235
	s_nop 0
	s_cbranch_vccnz .Lattn_redo_T30
	v_add_f32_e32 v167, v167, v190
	s_cmp_lg_u32 s14, 0
	s_cbranch_scc1 .Lattn_tb15
	s_cmp_lg_u32 s35, 0
	s_cbranch_scc1 .Lattn_tb15_w6
	s_waitcnt vmcnt(0)
	s_branch .Lattn_tb15_wd
.Lattn_tb15_w6:
	s_waitcnt vmcnt(8)

.Lattn_tb16:
	ds_read_b128 v[208:211], v187 offset:49152
	ds_read_b128 v[212:215], v187 offset:53248
	ds_read_b128 v[216:219], v187 offset:57344
	ds_read_b128 v[220:223], v187 offset:61440
	ds_read_b128 v[224:227], v188 offset:49152
	ds_read_b128 v[228:231], v188 offset:53248
	v_exp_f32_e32 v171, v96
	v_exp_f32_e32 v173, v97
	v_exp_f32_e32 v179, v98
	s_cmp_lg_u32 s35, 0
	s_cbranch_scc0 .Lattn_pfvu_f
	s_add_i32 s2, s31, 1
	s_and_b32 s2, s2, 31
	s_lshl_b32 s2, s2, 7
	s_add_i32 m0, s5, 81920
	s_add_u32 s44, s10, s2
	s_addc_u32 s45, s11, 0
	s_add_u32 s44, s44, 0x2000
	s_addc_u32 s45, s45, 0
	global_load_lds_dwordx4 v172, s[44:45]
	s_add_i32 m0, s5, 90112
	s_add_u32 s44, s44, 0x204000
	s_addc_u32 s45, s45, 0
	global_load_lds_dwordx4 v172, s[44:45]
.Lattn_pfvu_f:
	v_exp_f32_e32 v180, v99
	v_exp_f32_e32 v232, v100
	v_exp_f32_e32 v233, v101
	s_cmp_lg_u32 s35, 0
	s_cbranch_scc0 .Lattn_pfq_f
	s_movk_i32 s2, 0x1100
	s_lshl_b32 s36, s14, 1
	v_mad_u32_u24 v72, v168, s2, v192
	s_add_i32 s36, s36, s30
	s_add_i32 s36, s36, 0x1100000
	s_nop 0
	v_add_u32_e32 v72, s36, v72
	s_nop 0
	global_load_dwordx4 v[64:67], v72, s[6:7]
	global_load_dwordx4 v[68:71], v72, s[6:7] offset:32
	global_load_dwordx4 v[136:139], v72, s[6:7] offset:64
	global_load_dwordx4 v[140:143], v72, s[6:7] offset:96
.Lattn_pfq_f:
	v_exp_f32_e32 v234, v102
	v_exp_f32_e32 v235, v103
	v_add_f32_e32 v190, v171, v173
	v_add_f32_e32 v191, v179, v180
	v_add_f32_e32 v190, v190, v232
	v_add_f32_e32 v191, v191, v233
	v_add_f32_e32 v190, v190, v234
	v_add_f32_e32 v191, v191, v235
	v_cvt_pk_bf16_f32 v144, v171, v173
	v_cvt_pk_bf16_f32 v145, v179, v180
	v_cvt_pk_bf16_f32 v146, v232, v233
	v_cvt_pk_bf16_f32 v147, v234, v235
	v_exp_f32_e32 v171, v104
	v_exp_f32_e32 v173, v105
	v_exp_f32_e32 v179, v106
	v_exp_f32_e32 v180, v107
	v_exp_f32_e32 v232, v108
	v_exp_f32_e32 v233, v109
	v_exp_f32_e32 v234, v110
	v_exp_f32_e32 v235, v111
	v_add_f32_e32 v190, v190, v171
	v_add_f32_e32 v191, v191, v173
	v_add_f32_e32 v190, v190, v179
	v_add_f32_e32 v191, v191, v180
	v_add_f32_e32 v190, v190, v232
	v_add_f32_e32 v191, v191, v233
	v_add_f32_e32 v190, v190, v234
	v_add_f32_e32 v191, v191, v235
	v_cvt_pk_bf16_f32 v148, v171, v173
	v_cvt_pk_bf16_f32 v149, v179, v180
	v_cvt_pk_bf16_f32 v150, v232, v233
	v_cvt_pk_bf16_f32 v151, v234, v235
	v_exp_f32_e32 v171, v112
	v_exp_f32_e32 v173, v113
	v_exp_f32_e32 v179, v114
	v_exp_f32_e32 v180, v115
	v_exp_f32_e32 v232, v116
	v_exp_f32_e32 v233, v117
	v_exp_f32_e32 v234, v118
	v_exp_f32_e32 v235, v119
	v_add_f32_e32 v190, v190, v171
	v_add_f32_e32 v191, v191, v173
	v_add_f32_e32 v190, v190, v179
	v_add_f32_e32 v191, v191, v180
	v_add_f32_e32 v190, v190, v232
	v_add_f32_e32 v191, v191, v233
	v_add_f32_e32 v190, v190, v234
	v_add_f32_e32 v191, v191, v235
	v_cvt_pk_bf16_f32 v152, v171, v173
	v_cvt_pk_bf16_f32 v153, v179, v180
	v_cvt_pk_bf16_f32 v154, v232, v233
	v_cvt_pk_bf16_f32 v155, v234, v235
	v_exp_f32_e32 v171, v120
	v_exp_f32_e32 v173, v121
	v_exp_f32_e32 v179, v122
	v_exp_f32_e32 v180, v123
	v_exp_f32_e32 v232, v124
	v_exp_f32_e32 v233, v125
	v_exp_f32_e32 v234, v126
	v_exp_f32_e32 v235, v127
	v_add_f32_e32 v190, v190, v171
	v_add_f32_e32 v191, v191, v173
	v_add_f32_e32 v190, v190, v179
	v_add_f32_e32 v191, v191, v180
	v_add_f32_e32 v190, v190, v232
	v_add_f32_e32 v191, v191, v233
	v_add_f32_e32 v190, v190, v234
	v_add_f32_e32 v191, v191, v235
	v_add_f32_e32 v190, v190, v191
	v_cmp_ngt_f32_e32 vcc, 0x71800000, v190
	v_cvt_pk_bf16_f32 v156, v171, v173
	v_cvt_pk_bf16_f32 v157, v179, v180
	v_cvt_pk_bf16_f32 v158, v232, v233
	v_cvt_pk_bf16_f32 v159, v234, v235
	s_nop 0
	s_cbranch_vccnz .Lattn_redo_T31
	v_add_f32_e32 v167, v167, v190

.Lattn_pfvt_s:
	v_max3_f32 v254, v254, v69, v70
	s_cmp_lg_u32 s35, 0
	s_cbranch_scc0 .Lattn_pfkc_s
	s_add_i32 s2, s31, 2
	s_and_b32 s2, s2, 31
	s_mul_i32 s2, s2, 0x44000
	s_add_i32 m0, s5, 32768
	s_add_u32 s40, s26, s2
	s_addc_u32 s41, s27, 0
	s_add_u32 s40, s40, 0x1100000
	s_addc_u32 s41, s41, 0
	global_load_lds_dwordx4 v170, s[40:41]
	s_add_i32 m0, s5, 40960
	s_add_u32 s40, s40, 0x80
	s_addc_u32 s41, s41, 0
	global_load_lds_dwordx4 v170, s[40:41]
.Lattn_pfkc_s:
	v_max3_f32 v255, v255, v85, v86
	v_max3_f32 v254, v254, v71, v72
	v_max3_f32 v255, v255, v87, v88
	v_max3_f32 v254, v254, v73, v74
	v_max3_f32 v255, v255, v89, v90
	v_max3_f32 v254, v254, v75, v76
	v_max3_f32 v255, v255, v91, v92
	v_max3_f32 v254, v254, v77, v78
	v_max3_f32 v255, v255, v93, v94
	v_max3_f32 v254, v254, v79, v95
	v_max_f32_e32 v254, v254, v255
	v_mov_b32_e32 v255, v254
	s_nop 1
	v_permlane32_swap_b32_e32 v254, v255
	v_max_f32_e32 v254, v254, v255
	v_add_f32_e32 v180, 0x4138aa3b, v175
	v_cmp_gt_f32_e32 vcc, v254, v180
	s_nop 1
	v_cndmask_b32_e32 v180, v175, v254, vcc
	v_sub_f32_e32 v255, v175, v180
	v_exp_f32_e32 v174, v255
	v_mov_b32_e32 v175, v180
	v_sub_f32_e32 v64, v64, v175
	v_sub_f32_e32 v65, v65, v175
	v_sub_f32_e32 v66, v66, v175
	v_sub_f32_e32 v67, v67, v175
	v_sub_f32_e32 v68, v68, v175
	v_sub_f32_e32 v69, v69, v175
	v_sub_f32_e32 v70, v70, v175
	v_sub_f32_e32 v71, v71, v175
	v_exp_f32_e32 v64, v64
	v_exp_f32_e32 v65, v65
	v_exp_f32_e32 v66, v66
	v_exp_f32_e32 v67, v67
	v_exp_f32_e32 v68, v68
	v_exp_f32_e32 v69, v69
	v_exp_f32_e32 v70, v70
	v_exp_f32_e32 v71, v71
	v_add_f32_e32 v190, v64, v65
	v_add_f32_e32 v191, v66, v67
	v_add_f32_e32 v190, v190, v68
	v_add_f32_e32 v191, v191, v69
	v_add_f32_e32 v190, v190, v70
	v_add_f32_e32 v191, v191, v71
	v_cvt_pk_bf16_f32 v144, v64, v65
	v_cvt_pk_bf16_f32 v145, v66, v67
	v_cvt_pk_bf16_f32 v146, v68, v69
	v_cvt_pk_bf16_f32 v147, v70, v71
	v_sub_f32_e32 v72, v72, v175
	v_sub_f32_e32 v73, v73, v175
	v_sub_f32_e32 v74, v74, v175
	v_sub_f32_e32 v75, v75, v175
	v_sub_f32_e32 v76, v76, v175
	v_sub_f32_e32 v77, v77, v175
	v_sub_f32_e32 v78, v78, v175
	v_sub_f32_e32 v79, v79, v175
	v_exp_f32_e32 v72, v72
	v_exp_f32_e32 v73, v73
	v_exp_f32_e32 v74, v74
	v_exp_f32_e32 v75, v75
	v_exp_f32_e32 v76, v76
	v_exp_f32_e32 v77, v77
	v_exp_f32_e32 v78, v78
	v_exp_f32_e32 v79, v79
	v_add_f32_e32 v190, v190, v72
	v_add_f32_e32 v191, v191, v73
	v_add_f32_e32 v190, v190, v74
	v_add_f32_e32 v191, v191, v75
	v_add_f32_e32 v190, v190, v76
	v_add_f32_e32 v191, v191, v77
	v_add_f32_e32 v190, v190, v78
	v_add_f32_e32 v191, v191, v79
	v_cvt_pk_bf16_f32 v148, v72, v73
	v_cvt_pk_bf16_f32 v149, v74, v75
	v_cvt_pk_bf16_f32 v150, v76, v77
	v_cvt_pk_bf16_f32 v151, v78, v79
	v_sub_f32_e32 v80, v80, v175
	v_sub_f32_e32 v81, v81, v175
	v_sub_f32_e32 v82, v82, v175
	v_sub_f32_e32 v83, v83, v175
	v_sub_f32_e32 v84, v84, v175
	v_sub_f32_e32 v85, v85, v175
	v_sub_f32_e32 v86, v86, v175
	v_sub_f32_e32 v87, v87, v175
	v_exp_f32_e32 v80, v80
	v_exp_f32_e32 v81, v81
	v_exp_f32_e32 v82, v82
	v_exp_f32_e32 v83, v83
	v_exp_f32_e32 v84, v84
	v_exp_f32_e32 v85, v85
	v_exp_f32_e32 v86, v86
	v_exp_f32_e32 v87, v87
	v_add_f32_e32 v190, v190, v80
	v_add_f32_e32 v191, v191, v81
	v_add_f32_e32 v190, v190, v82
	v_add_f32_e32 v191, v191, v83
	v_add_f32_e32 v190, v190, v84
	v_add_f32_e32 v191, v191, v85
	v_add_f32_e32 v190, v190, v86
	v_add_f32_e32 v191, v191, v87
	v_cvt_pk_bf16_f32 v152, v80, v81
	v_cvt_pk_bf16_f32 v153, v82, v83
	v_cvt_pk_bf16_f32 v154, v84, v85
	v_cvt_pk_bf16_f32 v155, v86, v87
	v_sub_f32_e32 v88, v88, v175
	v_sub_f32_e32 v89, v89, v175
	v_sub_f32_e32 v90, v90, v175
	v_sub_f32_e32 v91, v91, v175
	v_sub_f32_e32 v92, v92, v175
	v_sub_f32_e32 v93, v93, v175
	v_sub_f32_e32 v94, v94, v175
	v_sub_f32_e32 v95, v95, v175
	v_exp_f32_e32 v88, v88
	v_exp_f32_e32 v89, v89
	v_exp_f32_e32 v90, v90
	v_exp_f32_e32 v91, v91
	v_exp_f32_e32 v92, v92
	v_exp_f32_e32 v93, v93
	v_exp_f32_e32 v94, v94
	v_exp_f32_e32 v95, v95
	v_add_f32_e32 v190, v190, v88
	v_add_f32_e32 v191, v191, v89
	v_add_f32_e32 v190, v190, v90
	v_add_f32_e32 v191, v191, v91
	v_add_f32_e32 v190, v190, v92
	v_add_f32_e32 v191, v191, v93
	v_add_f32_e32 v190, v190, v94
	v_add_f32_e32 v191, v191, v95
	v_cvt_pk_bf16_f32 v156, v88, v89
	v_cvt_pk_bf16_f32 v157, v90, v91
	v_cvt_pk_bf16_f32 v158, v92, v93
	v_cvt_pk_bf16_f32 v159, v94, v95
	v_add_f32_e32 v190, v190, v191
	v_fma_f32 v167, v167, v174, v190
	s_cbranch_vccz .Lattn_noresc_T30
	s_nop 7
	s_nop 7
	v_pk_mul_f32 v[0:1], v[0:1], v[174:175] op_sel_hi:[1,0]
	v_pk_mul_f32 v[2:3], v[2:3], v[174:175] op_sel_hi:[1,0]
	v_pk_mul_f32 v[4:5], v[4:5], v[174:175] op_sel_hi:[1,0]
	v_pk_mul_f32 v[6:7], v[6:7], v[174:175] op_sel_hi:[1,0]
	v_pk_mul_f32 v[8:9], v[8:9], v[174:175] op_sel_hi:[1,0]
	v_pk_mul_f32 v[10:11], v[10:11], v[174:175] op_sel_hi:[1,0]
	v_pk_mul_f32 v[12:13], v[12:13], v[174:175] op_sel_hi:[1,0]
	v_pk_mul_f32 v[14:15], v[14:15], v[174:175] op_sel_hi:[1,0]
	v_pk_mul_f32 v[16:17], v[16:17], v[174:175] op_sel_hi:[1,0]
	v_pk_mul_f32 v[18:19], v[18:19], v[174:175] op_sel_hi:[1,0]
	v_pk_mul_f32 v[20:21], v[20:21], v[174:175] op_sel_hi:[1,0]
	v_pk_mul_f32 v[22:23], v[22:23], v[174:175] op_sel_hi:[1,0]
	v_pk_mul_f32 v[24:25], v[24:25], v[174:175] op_sel_hi:[1,0]
	v_pk_mul_f32 v[26:27], v[26:27], v[174:175] op_sel_hi:[1,0]
	v_pk_mul_f32 v[28:29], v[28:29], v[174:175] op_sel_hi:[1,0]
	v_pk_mul_f32 v[30:31], v[30:31], v[174:175] op_sel_hi:[1,0]
	v_pk_mul_f32 v[32:33], v[32:33], v[174:175] op_sel_hi:[1,0]
	v_pk_mul_f32 v[34:35], v[34:35], v[174:175] op_sel_hi:[1,0]
	v_pk_mul_f32 v[36:37], v[36:37], v[174:175] op_sel_hi:[1,0]
	v_pk_mul_f32 v[38:39], v[38:39], v[174:175] op_sel_hi:[1,0]
	v_pk_mul_f32 v[40:41], v[40:41], v[174:175] op_sel_hi:[1,0]
	v_pk_mul_f32 v[42:43], v[42:43], v[174:175] op_sel_hi:[1,0]
	v_pk_mul_f32 v[44:45], v[44:45], v[174:175] op_sel_hi:[1,0]
	v_pk_mul_f32 v[46:47], v[46:47], v[174:175] op_sel_hi:[1,0]
	v_pk_mul_f32 v[48:49], v[48:49], v[174:175] op_sel_hi:[1,0]
	v_pk_mul_f32 v[50:51], v[50:51], v[174:175] op_sel_hi:[1,0]
	v_pk_mul_f32 v[52:53], v[52:53], v[174:175] op_sel_hi:[1,0]
	v_pk_mul_f32 v[54:55], v[54:55], v[174:175] op_sel_hi:[1,0]
	v_pk_mul_f32 v[56:57], v[56:57], v[174:175] op_sel_hi:[1,0]
	v_pk_mul_f32 v[58:59], v[58:59], v[174:175] op_sel_hi:[1,0]
	v_pk_mul_f32 v[60:61], v[60:61], v[174:175] op_sel_hi:[1,0]
	v_pk_mul_f32 v[62:63], v[62:63], v[174:175] op_sel_hi:[1,0]
	s_nop 1

.Lattn_tb32:
	ds_read_b128 v[208:211], v187 offset:49152
	ds_read_b128 v[212:215], v187 offset:53248
	ds_read_b128 v[216:219], v187 offset:57344
	ds_read_b128 v[220:223], v187 offset:61440
	ds_read_b128 v[224:227], v188 offset:49152
	ds_read_b128 v[228:231], v188 offset:53248
	v_max3_f32 v254, v96, v97, v98
	s_cmp_lg_u32 s35, 0
	s_cbranch_scc0 .Lattn_pfvu_s
	s_add_i32 s2, s31, 1
	s_and_b32 s2, s2, 31
	s_lshl_b32 s2, s2, 7
	s_add_i32 m0, s5, 81920
	s_add_u32 s44, s10, s2
	s_addc_u32 s45, s11, 0
	s_add_u32 s44, s44, 0x2000
	s_addc_u32 s45, s45, 0
	global_load_lds_dwordx4 v172, s[44:45]
	s_add_i32 m0, s5, 90112
	s_add_u32 s44, s44, 0x204000
	s_addc_u32 s45, s45, 0
	global_load_lds_dwordx4 v172, s[44:45]
.Lattn_pfvu_s:
	v_max3_f32 v255, v112, v113, v114
	s_cmp_lg_u32 s35, 0
	s_cbranch_scc0 .Lattn_pfq_s
	s_movk_i32 s2, 0x1100
	s_lshl_b32 s36, s14, 1
	v_mad_u32_u24 v72, v168, s2, v192
	s_add_i32 s36, s36, s30
	s_add_i32 s36, s36, 0x1100000
	s_nop 0
	v_add_u32_e32 v72, s36, v72
	s_nop 0
	global_load_dwordx4 v[64:67], v72, s[6:7]
	global_load_dwordx4 v[68:71], v72, s[6:7] offset:32
	global_load_dwordx4 v[136:139], v72, s[6:7] offset:64
	global_load_dwordx4 v[140:143], v72, s[6:7] offset:96
.Lattn_pfq_s:
	v_max3_f32 v254, v254, v99, v100
	v_max3_f32 v255, v255, v115, v116
	v_max3_f32 v254, v254, v101, v102
	v_max3_f32 v255, v255, v117, v118
	v_max3_f32 v254, v254, v103, v104
	v_max3_f32 v255, v255, v119, v120
	v_max3_f32 v254, v254, v105, v106
	v_max3_f32 v255, v255, v121, v122
	v_max3_f32 v254, v254, v107, v108
	v_max3_f32 v255, v255, v123, v124
	v_max3_f32 v254, v254, v109, v110
	v_max3_f32 v255, v255, v125, v126
	v_max3_f32 v254, v254, v111, v127
	v_max_f32_e32 v254, v254, v255
	v_mov_b32_e32 v255, v254
	s_nop 1
	v_permlane32_swap_b32_e32 v254, v255
	v_max_f32_e32 v254, v254, v255
	v_add_f32_e32 v180, 0x4138aa3b, v175
	v_cmp_gt_f32_e32 vcc, v254, v180
	s_nop 1
	v_cndmask_b32_e32 v180, v175, v254, vcc
	v_sub_f32_e32 v255, v175, v180
	v_exp_f32_e32 v174, v255
	v_mov_b32_e32 v175, v180
	v_sub_f32_e32 v96, v96, v175
	v_sub_f32_e32 v97, v97, v175
	v_sub_f32_e32 v98, v98, v175
	v_sub_f32_e32 v99, v99, v175
	v_sub_f32_e32 v100, v100, v175
	v_sub_f32_e32 v101, v101, v175
	v_sub_f32_e32 v102, v102, v175
	v_sub_f32_e32 v103, v103, v175
	v_exp_f32_e32 v96, v96
	v_exp_f32_e32 v97, v97
	v_exp_f32_e32 v98, v98
	v_exp_f32_e32 v99, v99
	v_exp_f32_e32 v100, v100
	v_exp_f32_e32 v101, v101
	v_exp_f32_e32 v102, v102
	v_exp_f32_e32 v103, v103
	v_add_f32_e32 v190, v96, v97
	v_add_f32_e32 v191, v98, v99
	v_add_f32_e32 v190, v190, v100
	v_add_f32_e32 v191, v191, v101
	v_add_f32_e32 v190, v190, v102
	v_add_f32_e32 v191, v191, v103
	v_cvt_pk_bf16_f32 v144, v96, v97
	v_cvt_pk_bf16_f32 v145, v98, v99
	v_cvt_pk_bf16_f32 v146, v100, v101
	v_cvt_pk_bf16_f32 v147, v102, v103
	v_sub_f32_e32 v104, v104, v175
	v_sub_f32_e32 v105, v105, v175
	v_sub_f32_e32 v106, v106, v175
	v_sub_f32_e32 v107, v107, v175
	v_sub_f32_e32 v108, v108, v175
	v_sub_f32_e32 v109, v109, v175
	v_sub_f32_e32 v110, v110, v175
	v_sub_f32_e32 v111, v111, v175
	v_exp_f32_e32 v104, v104
	v_exp_f32_e32 v105, v105
	v_exp_f32_e32 v106, v106
	v_exp_f32_e32 v107, v107
	v_exp_f32_e32 v108, v108
	v_exp_f32_e32 v109, v109
	v_exp_f32_e32 v110, v110
	v_exp_f32_e32 v111, v111
	v_add_f32_e32 v190, v190, v104
	v_add_f32_e32 v191, v191, v105
	v_add_f32_e32 v190, v190, v106
	v_add_f32_e32 v191, v191, v107
	v_add_f32_e32 v190, v190, v108
	v_add_f32_e32 v191, v191, v109
	v_add_f32_e32 v190, v190, v110
	v_add_f32_e32 v191, v191, v111
	v_cvt_pk_bf16_f32 v148, v104, v105
	v_cvt_pk_bf16_f32 v149, v106, v107
	v_cvt_pk_bf16_f32 v150, v108, v109
	v_cvt_pk_bf16_f32 v151, v110, v111
	v_sub_f32_e32 v112, v112, v175
	v_sub_f32_e32 v113, v113, v175
	v_sub_f32_e32 v114, v114, v175
	v_sub_f32_e32 v115, v115, v175
	v_sub_f32_e32 v116, v116, v175
	v_sub_f32_e32 v117, v117, v175
	v_sub_f32_e32 v118, v118, v175
	v_sub_f32_e32 v119, v119, v175
	v_exp_f32_e32 v112, v112
	v_exp_f32_e32 v113, v113
	v_exp_f32_e32 v114, v114
	v_exp_f32_e32 v115, v115
	v_exp_f32_e32 v116, v116
	v_exp_f32_e32 v117, v117
	v_exp_f32_e32 v118, v118
	v_exp_f32_e32 v119, v119
	v_add_f32_e32 v190, v190, v112
	v_add_f32_e32 v191, v191, v113
	v_add_f32_e32 v190, v190, v114
	v_add_f32_e32 v191, v191, v115
	v_add_f32_e32 v190, v190, v116
	v_add_f32_e32 v191, v191, v117
	v_add_f32_e32 v190, v190, v118
	v_add_f32_e32 v191, v191, v119
	v_cvt_pk_bf16_f32 v152, v112, v113
	v_cvt_pk_bf16_f32 v153, v114, v115
	v_cvt_pk_bf16_f32 v154, v116, v117
	v_cvt_pk_bf16_f32 v155, v118, v119
	v_sub_f32_e32 v120, v120, v175
	v_sub_f32_e32 v121, v121, v175
	v_sub_f32_e32 v122, v122, v175
	v_sub_f32_e32 v123, v123, v175
	v_sub_f32_e32 v124, v124, v175
	v_sub_f32_e32 v125, v125, v175
	v_sub_f32_e32 v126, v126, v175
	v_sub_f32_e32 v127, v127, v175
	v_exp_f32_e32 v120, v120
	v_exp_f32_e32 v121, v121
	v_exp_f32_e32 v122, v122
	v_exp_f32_e32 v123, v123
	v_exp_f32_e32 v124, v124
	v_exp_f32_e32 v125, v125
	v_exp_f32_e32 v126, v126
	v_exp_f32_e32 v127, v127
	v_add_f32_e32 v190, v190, v120
	v_add_f32_e32 v191, v191, v121
	v_add_f32_e32 v190, v190, v122
	v_add_f32_e32 v191, v191, v123
	v_add_f32_e32 v190, v190, v124
	v_add_f32_e32 v191, v191, v125
	v_add_f32_e32 v190, v190, v126
	v_add_f32_e32 v191, v191, v127
	v_cvt_pk_bf16_f32 v156, v120, v121
	v_cvt_pk_bf16_f32 v157, v122, v123
	v_cvt_pk_bf16_f32 v158, v124, v125
	v_cvt_pk_bf16_f32 v159, v126, v127
	v_add_f32_e32 v190, v190, v191
	v_fma_f32 v167, v167, v174, v190
	s_cbranch_vccz .Lattn_noresc_T31
	s_nop 7
	s_nop 7
	v_pk_mul_f32 v[0:1], v[0:1], v[174:175] op_sel_hi:[1,0]
	v_pk_mul_f32 v[2:3], v[2:3], v[174:175] op_sel_hi:[1,0]
	v_pk_mul_f32 v[4:5], v[4:5], v[174:175] op_sel_hi:[1,0]
	v_pk_mul_f32 v[6:7], v[6:7], v[174:175] op_sel_hi:[1,0]
	v_pk_mul_f32 v[8:9], v[8:9], v[174:175] op_sel_hi:[1,0]
	v_pk_mul_f32 v[10:11], v[10:11], v[174:175] op_sel_hi:[1,0]
	v_pk_mul_f32 v[12:13], v[12:13], v[174:175] op_sel_hi:[1,0]
	v_pk_mul_f32 v[14:15], v[14:15], v[174:175] op_sel_hi:[1,0]
	v_pk_mul_f32 v[16:17], v[16:17], v[174:175] op_sel_hi:[1,0]
	v_pk_mul_f32 v[18:19], v[18:19], v[174:175] op_sel_hi:[1,0]
	v_pk_mul_f32 v[20:21], v[20:21], v[174:175] op_sel_hi:[1,0]
	v_pk_mul_f32 v[22:23], v[22:23], v[174:175] op_sel_hi:[1,0]
	v_pk_mul_f32 v[24:25], v[24:25], v[174:175] op_sel_hi:[1,0]
	v_pk_mul_f32 v[26:27], v[26:27], v[174:175] op_sel_hi:[1,0]
	v_pk_mul_f32 v[28:29], v[28:29], v[174:175] op_sel_hi:[1,0]
	v_pk_mul_f32 v[30:31], v[30:31], v[174:175] op_sel_hi:[1,0]
	v_pk_mul_f32 v[32:33], v[32:33], v[174:175] op_sel_hi:[1,0]
	v_pk_mul_f32 v[34:35], v[34:35], v[174:175] op_sel_hi:[1,0]
	v_pk_mul_f32 v[36:37], v[36:37], v[174:175] op_sel_hi:[1,0]
	v_pk_mul_f32 v[38:39], v[38:39], v[174:175] op_sel_hi:[1,0]
	v_pk_mul_f32 v[40:41], v[40:41], v[174:175] op_sel_hi:[1,0]
	v_pk_mul_f32 v[42:43], v[42:43], v[174:175] op_sel_hi:[1,0]
	v_pk_mul_f32 v[44:45], v[44:45], v[174:175] op_sel_hi:[1,0]
	v_pk_mul_f32 v[46:47], v[46:47], v[174:175] op_sel_hi:[1,0]
	v_pk_mul_f32 v[48:49], v[48:49], v[174:175] op_sel_hi:[1,0]
	v_pk_mul_f32 v[50:51], v[50:51], v[174:175] op_sel_hi:[1,0]
	v_pk_mul_f32 v[52:53], v[52:53], v[174:175] op_sel_hi:[1,0]
	v_pk_mul_f32 v[54:55], v[54:55], v[174:175] op_sel_hi:[1,0]
	v_pk_mul_f32 v[56:57], v[56:57], v[174:175] op_sel_hi:[1,0]
	v_pk_mul_f32 v[58:59], v[58:59], v[174:175] op_sel_hi:[1,0]
	v_pk_mul_f32 v[60:61], v[60:61], v[174:175] op_sel_hi:[1,0]
	v_pk_mul_f32 v[62:63], v[62:63], v[174:175] op_sel_hi:[1,0]
	s_nop 1

.Lattn_end:
	s_barrier
	ds_bpermute_b32 v65, v165, v64
	s_and_b64 vcc, exec, s[28:29]
	s_waitcnt lgkmcnt(0)
	v_add_f32_e32 v64, v64, v65
	s_cbranch_vccz .LBB0_651
	v_div_scale_f32 v65, s[40:41], v64, v64, v177
	v_rcp_f32_e32 v66, v65
	v_div_scale_f32 v67, vcc, v177, v64, v177
	v_fma_f32 v68, -v65, v66, 1.0
	v_fmac_f32_e32 v66, v68, v66
	v_mul_f32_e32 v68, v67, v66
	v_fma_f32 v69, -v65, v68, v67
	v_fmac_f32_e32 v68, v69, v66
	v_fma_f32 v65, -v65, v68, v67
	v_div_fmas_f32 v65, v65, v66, v68
	v_div_fixup_f32 v65, v65, v64, v177
	v_mul_f32_e32 v66, v48, v65
	v_mul_f32_e32 v67, v49, v65
	ds_write2st64_b32 v181, v66, v67 offset1:1
	v_mul_f32_e32 v66, v50, v65
	v_mul_f32_e32 v67, v51, v65
	ds_write2st64_b32 v181, v66, v67 offset0:2 offset1:3
	v_mul_f32_e32 v66, v52, v65
	v_mul_f32_e32 v67, v53, v65
	ds_write2st64_b32 v181, v66, v67 offset0:4 offset1:5
	v_mul_f32_e32 v66, v54, v65
	v_mul_f32_e32 v67, v55, v65
	ds_write2st64_b32 v181, v66, v67 offset0:6 offset1:7
	v_mul_f32_e32 v66, v56, v65
	v_mul_f32_e32 v67, v57, v65
	ds_write2st64_b32 v181, v66, v67 offset0:8 offset1:9
	v_mul_f32_e32 v66, v58, v65
	v_mul_f32_e32 v67, v59, v65
	ds_write2st64_b32 v181, v66, v67 offset0:10 offset1:11
	v_mul_f32_e32 v66, v60, v65
	v_mul_f32_e32 v67, v61, v65
	ds_write2st64_b32 v181, v66, v67 offset0:12 offset1:13
	v_mul_f32_e32 v66, v62, v65
	v_mul_f32_e32 v67, v63, v65
	ds_write2st64_b32 v181, v66, v67 offset0:14 offset1:15
	v_mul_f32_e32 v66, v32, v65
	v_mul_f32_e32 v67, v33, v65
	ds_write2st64_b32 v181, v66, v67 offset0:16 offset1:17
	v_mul_f32_e32 v66, v34, v65
	v_mul_f32_e32 v67, v35, v65
	ds_write2st64_b32 v181, v66, v67 offset0:18 offset1:19
	v_mul_f32_e32 v66, v36, v65
	v_mul_f32_e32 v67, v37, v65
	ds_write2st64_b32 v181, v66, v67 offset0:20 offset1:21
	v_mul_f32_e32 v66, v38, v65
	v_mul_f32_e32 v67, v39, v65
	ds_write2st64_b32 v181, v66, v67 offset0:22 offset1:23
	v_mul_f32_e32 v66, v40, v65
	v_mul_f32_e32 v67, v41, v65
	ds_write2st64_b32 v181, v66, v67 offset0:24 offset1:25
	v_mul_f32_e32 v66, v42, v65
	v_mul_f32_e32 v67, v43, v65
	ds_write2st64_b32 v181, v66, v67 offset0:26 offset1:27
	v_mul_f32_e32 v66, v44, v65
	v_mul_f32_e32 v67, v45, v65
	ds_write2st64_b32 v181, v66, v67 offset0:28 offset1:29
	v_mul_f32_e32 v66, v46, v65
	v_mul_f32_e32 v67, v47, v65
	ds_write2st64_b32 v181, v66, v67 offset0:30 offset1:31
	v_mul_f32_e32 v66, v16, v65
	v_mul_f32_e32 v67, v17, v65
	ds_write2st64_b32 v181, v66, v67 offset0:32 offset1:33
	v_mul_f32_e32 v66, v18, v65
	v_mul_f32_e32 v67, v19, v65
	ds_write2st64_b32 v181, v66, v67 offset0:34 offset1:35
	v_mul_f32_e32 v66, v20, v65
	v_mul_f32_e32 v67, v21, v65
	ds_write2st64_b32 v181, v66, v67 offset0:36 offset1:37
	v_mul_f32_e32 v66, v22, v65
	v_mul_f32_e32 v67, v23, v65
	ds_write2st64_b32 v181, v66, v67 offset0:38 offset1:39
	v_mul_f32_e32 v66, v24, v65
	v_mul_f32_e32 v67, v25, v65
	ds_write2st64_b32 v181, v66, v67 offset0:40 offset1:41
	v_mul_f32_e32 v66, v26, v65
	v_mul_f32_e32 v67, v27, v65
	ds_write2st64_b32 v181, v66, v67 offset0:42 offset1:43
	v_mul_f32_e32 v66, v28, v65
	v_mul_f32_e32 v67, v29, v65
	ds_write2st64_b32 v181, v66, v67 offset0:44 offset1:45
	v_mul_f32_e32 v66, v30, v65
	v_mul_f32_e32 v67, v31, v65
	ds_write2st64_b32 v181, v66, v67 offset0:46 offset1:47
	v_mul_f32_e32 v66, v0, v65
	v_mul_f32_e32 v67, v1, v65
	ds_write2st64_b32 v181, v66, v67 offset0:48 offset1:49
	v_mul_f32_e32 v66, v2, v65
	v_mul_f32_e32 v67, v3, v65
	ds_write2st64_b32 v181, v66, v67 offset0:50 offset1:51
	v_mul_f32_e32 v66, v4, v65
	v_mul_f32_e32 v67, v5, v65
	ds_write2st64_b32 v181, v66, v67 offset0:52 offset1:53
	v_mul_f32_e32 v66, v6, v65
	v_mul_f32_e32 v67, v7, v65
	ds_write2st64_b32 v181, v66, v67 offset0:54 offset1:55
	v_mul_f32_e32 v66, v8, v65
	v_mul_f32_e32 v67, v9, v65
	ds_write2st64_b32 v181, v66, v67 offset0:56 offset1:57
	v_mul_f32_e32 v66, v10, v65
	v_mul_f32_e32 v67, v11, v65
	ds_write2st64_b32 v181, v66, v67 offset0:58 offset1:59
	v_mul_f32_e32 v66, v12, v65
	v_mul_f32_e32 v67, v13, v65
	ds_write2st64_b32 v181, v66, v67 offset0:60 offset1:61
	v_mul_f32_e32 v66, v14, v65
	v_mul_f32_e32 v65, v15, v65
	ds_write2st64_b32 v181, v66, v65 offset0:62 offset1:63
